# unit-order rotation in P2/P10/P13: odd XCDs take their K-eighth sub-unit first, so the two halves' epilogue bursts are offset by a sub-unit time
# speedup vs baseline: 1.0087x; 1.0036x over previous
.LBB0_289:
	s_add_u32 s0, s34, 0x2e400000
	s_addc_u32 s1, s35, 0
	v_writelane_b32 v254, s0, 41
	s_nop 1
	v_writelane_b32 v254, s1, 42
	s_add_u32 s0, s34, 0x52600000
	s_addc_u32 s1, s35, 0
	v_writelane_b32 v254, s0, 43
	s_cmp_lt_i32 s20, 3
	s_nop 0
	v_writelane_b32 v254, s1, 44
	s_cselect_b64 s[0:1], -1, 0
	s_cmp_gt_i32 s21, 2
	s_cselect_b64 s[2:3], -1, 0
	s_and_b64 s[0:1], s[0:1], s[2:3]
	s_andn2_b64 vcc, exec, s[0:1]
	s_cbranch_vccnz .LBB0_449
	s_cmpk_lg_i32 s33, 0x100
	s_cbranch_scc1 .Lrot2_f
	v_readlane_b32 s0, v254, 15
	s_nop 3
	s_bitcmp1_b32 s0, 5
	s_cbranch_scc0 .Lrot2_f
	s_add_i32 s95, s95, 0x200
.Lrot2_f:
	v_mbcnt_lo_u32_b32 v0, -1, 0
	v_mbcnt_hi_u32_b32 v0, -1, v0
	s_movk_i32 s12, 0x1580
	s_cmpk_gt_i32 s95, 0x1ff
	v_mbcnt_lo_u32_b32 v0, -1, 0
	v_mbcnt_hi_u32_b32 v0, -1, v0
	s_cbranch_scc0 .LBB0_293
	s_add_i32 s10, s95, 0xfffffe00
	s_cmpk_gt_u32 s10, 0xff
	s_mov_b64 s[4:5], 0
	s_cbranch_scc1 .LBB0_294
	s_and_b32 s0, s95, 7
	s_lshr_b32 s1, s10, 3
	s_cmpk_gt_u32 s10, 0x7f
	s_cselect_b32 s7, 33, 32
	s_add_i32 s2, s1, -16
	s_cmpk_lt_u32 s10, 0x80
	s_cselect_b32 s6, s1, s2
	s_min_u32 s1, s0, 3
	s_cmp_gt_u32 s0, 2
	s_cselect_b32 s13, 10, 12
	s_lshl_b32 s1, s1, 8
	s_mulk_i32 s0, 0x500
	s_add_i32 s2, s1, s0
	s_mov_b64 s[0:1], -1
	s_andn2_b64 vcc, exec, s[4:5]
	s_cbranch_vccz .LBB0_295
	s_branch .LBB0_300

.LBB0_306:
	s_add_i32 s20, s20, 1
	s_mul_i32 s0, s20, s88
	s_mul_hi_u32 s1, s20, s33
	s_add_i32 s1, s1, s0
	s_mul_i32 s0, s20, s33
	v_readlane_b32 s4, v254, 22
	s_add_u32 s0, s0, s4
	s_addc_u32 s1, s1, s89
	s_cmpk_lg_i32 s33, 0x100
	s_cbranch_scc1 .Lrot2_h
	v_readlane_b32 s4, v254, 15
	s_nop 3
	s_bitcmp1_b32 s4, 5
	s_cbranch_scc0 .Lrot2_h
	s_cmp_lg_u32 s1, 0
	s_cbranch_scc1 .Lrot2_h
	s_cmpk_ge_u32 s0, 0x300
	s_cbranch_scc1 .Lrot2_h
	s_add_u32 s0, s0, 0x200
	s_cmpk_lt_u32 s0, 0x300
	s_cbranch_scc1 .Lrot2_h
	s_sub_u32 s0, s0, 0x300
.Lrot2_h:
	v_mov_b64_e32 v[0:1], 0x1ff
	v_cmp_gt_i64_e32 vcc, s[0:1], v[0:1]
	s_mov_b64 s[4:5], -1
	s_cbranch_vccz .LBB0_309
	s_add_i32 s1, s0, 0xfffffe00
	s_mov_b64 s[4:5], 0
	s_cmpk_gt_i32 s1, 0xff
	s_mov_b64 s[70:71], 0
	s_cbranch_scc1 .LBB0_309
	s_ashr_i32 s22, s1, 3
	s_lshr_b32 s12, s22, 28
	s_add_i32 s23, s22, s12
	s_and_b32 s13, s0, 7
	s_ashr_i32 s12, s23, 4
	s_and_b32 s23, s23, -16
	s_sub_i32 s43, s22, s23
	s_min_u32 s23, s13, 3
	s_mul_i32 s22, s13, 10
	s_lshl_b32 s23, s23, 1
	s_add_i32 s12, s12, 32
	s_add_i32 s45, s23, s22
	s_cmp_gt_u32 s13, 2
	s_cselect_b32 s13, 10, 12
	s_mov_b64 s[70:71], -1
	s_mov_b32 s91, s1

.LBB0_1372:
	s_cmp_lt_i32 s92, 11
	s_cselect_b64 s[0:1], -1, 0
	s_cmp_gt_i32 s93, 10
	s_cselect_b64 s[2:3], -1, 0
	s_and_b64 s[0:1], s[0:1], s[2:3]
	s_andn2_b64 vcc, exec, s[0:1]
	v_readlane_b32 s70, v254, 47
	s_cbranch_vccnz .LBB0_1468
	s_cmpk_lg_i32 s33, 0x100
	s_cbranch_scc1 .Lrot10_f
	v_readlane_b32 s0, v254, 15
	s_nop 3
	s_bitcmp1_b32 s0, 5
	s_cbranch_scc0 .Lrot10_f
	s_add_i32 s95, s95, 0x200
.Lrot10_f:
	s_waitcnt vmcnt(31)
	v_mbcnt_lo_u32_b32 v0, -1, 0
	v_mbcnt_hi_u32_b32 v0, -1, v0
	s_movk_i32 s2, 0x1000
	v_mbcnt_lo_u32_b32 v0, -1, 0
	v_mbcnt_hi_u32_b32 v0, -1, v0
	s_ashr_i32 s0, s2, 31
	s_lshr_b32 s0, s0, 26
	s_add_i32 s2, s2, s0
	s_cmpk_gt_i32 s95, 0x1ff
	s_cbranch_scc0 .LBB0_1379
	s_add_i32 s0, s95, 0xfffffe00
	v_readlane_b32 s54, v254, 48
	s_mov_b64 s[6:7], 0
	s_cmpk_lt_u32 s0, 0x100
	s_mov_b64 s[4:5], 0
	v_readlane_b32 s55, v254, 49
	s_cbranch_scc0 .LBB0_1376
	s_lshr_b32 s1, s0, 3
	s_cmpk_gt_u32 s0, 0x7f
	s_cselect_b32 s56, 33, 32
	s_add_i32 s3, s1, -16
	s_cmpk_lt_u32 s0, 0x80
	s_cselect_b32 s11, s1, s3
	s_lshl_b32 s1, s95, 10
	s_and_b32 s1, s1, 0x1c00
	s_mov_b64 s[4:5], -1
	s_ashr_i32 s2, s2, 6
	s_mov_b32 s57, 8
	s_and_b64 vcc, exec, s[6:7]
	s_cbranch_vccz .LBB0_1380
	s_branch .LBB0_1377

.LBB0_1383:
	s_add_i32 s26, s3, 0x18000
	s_or_b32 s7, s22, 0x80
	s_mov_b32 s38, s14
	s_mov_b32 s39, s15
	s_mov_b32 m0, s26
	s_add_i32 s27, s3, 0x1a000
	s_waitcnt vmcnt(2)
	s_barrier
	buffer_load_dwordx4 v139, s[36:39], s7 offen lds
	s_mov_b32 m0, s27
	s_add_i32 s29, s3, 0x8000
	buffer_load_dwordx4 v141, s[36:39], s7 offen lds
	s_or_b32 s7, s23, 0x80
	s_mov_b32 m0, s29
	s_add_i32 s30, s3, 0xa000
	buffer_load_dwordx4 v138, s[12:15], s7 offen lds
	s_mov_b32 m0, s30
	s_add_i32 s31, s3, 0x1c000
	buffer_load_dwordx4 v140, s[12:15], s7 offen lds
	s_or_b32 s7, s22, 0x100080
	s_mov_b32 m0, s31
	s_add_i32 s40, s3, 0x1e000
	buffer_load_dwordx4 v139, s[36:39], s7 offen lds
	s_mov_b32 m0, s40
	s_lshl_b32 s41, s6, 6
	buffer_load_dwordx4 v141, s[36:39], s7 offen lds
	v_ashrrev_i32_e32 v1, 6, v0
	s_lshl_b32 s6, s6, 13
	v_and_b32_e32 v2, 48, v0
	v_lshl_add_u32 v3, v1, 10, s6
	v_lshlrev_b32_e32 v4, 6, v0
	s_movk_i32 s6, 0x3c0
	v_and_or_b32 v2, v4, s6, v2
	v_readlane_b32 s6, v254, 16
	s_lshl_b32 s6, s6, 5
	s_and_b32 s42, s6, 0x60
	v_lshlrev_b32_e32 v0, 2, v0
	s_lshr_b32 s6, s42, 3
	v_and_b32_e32 v0, 32, v0
	v_add_lshl_u32 v1, v1, s6, 10
	v_bitop3_b32 v3, v2, v3, v0 bitop3:0xde
	v_bitop3_b32 v0, v2, v1, v0 bitop3:0xde
	s_waitcnt vmcnt(6)
	s_add_i32 s43, s3, 0xc000
	s_mov_b64 s[62:63], s[14:15]
	s_cmpk_lt_u32 s89, 0x100
	v_add_u32_e32 v0, 0, v0
	s_mov_b64 s[60:61], s[12:13]
	s_cselect_b64 s[6:7], -1, 0
	s_add_i32 s44, s3, 0xe000
	s_ashr_i32 s45, s33, 31
	s_ashr_i32 s46, s95, 31
	v_mov_b64_e32 v[128:129], 0x1ff
	s_cmpk_lg_i32 s33, 0x100
	s_cbranch_scc1 .Lrot10_r
	v_readlane_b32 s8, v254, 15
	s_nop 3
	s_bitcmp1_b32 s8, 5
	s_cbranch_scc0 .Lrot10_r
	s_sub_i32 s95, s95, 0x200
.Lrot10_r:
	v_add_u32_e32 v142, 0x10000, v0
	v_add_u32_e32 v143, 0x14000, v0
	v_add_u32_e32 v144, 0, v3
	v_add_u32_e32 v145, 0x18000, v0
	v_add_u32_e32 v146, 0x1c000, v0
	s_mov_b32 s8, 0x3f9837f0
	v_mov_b32_e32 v131, 0
	s_lshl_b32 s10, s42, 2
	s_mov_b32 s47, s1
	s_barrier
	s_branch .LBB0_1386

.LBB0_1386:
	s_add_i32 s47, s47, 1
	s_mul_i32 s12, s47, s45
	s_mul_hi_u32 s13, s47, s33
	s_add_i32 s13, s13, s12
	s_mul_i32 s12, s47, s33
	s_add_u32 s14, s12, s95
	s_addc_u32 s15, s13, s46
	s_cmpk_lg_i32 s33, 0x100
	s_cbranch_scc1 .Lrot10_h
	v_readlane_b32 s16, v254, 15
	s_nop 3
	s_bitcmp1_b32 s16, 5
	s_cbranch_scc0 .Lrot10_h
	s_cmp_lg_u32 s15, 0
	s_cbranch_scc1 .Lrot10_h
	s_cmpk_ge_u32 s14, 0x300
	s_cbranch_scc1 .Lrot10_h
	s_add_u32 s14, s14, 0x200
	s_cmpk_lt_u32 s14, 0x300
	s_cbranch_scc1 .Lrot10_h
	s_sub_u32 s14, s14, 0x300
.Lrot10_h:
	v_cmp_gt_i64_e32 vcc, s[14:15], v[128:129]
	s_mov_b64 s[16:17], -1
	s_cbranch_vccz .LBB0_1389
	s_add_i32 s15, s14, 0xfffffe00
	s_mov_b64 s[16:17], 0
	s_cmpk_gt_i32 s15, 0xff
	s_mov_b64 s[12:13], 0
	s_cbranch_scc1 .LBB0_1389
	s_lshl_b32 s12, s14, 3
	s_and_b32 s49, s12, 56
	s_ashr_i32 s12, s15, 3
	s_lshr_b32 s13, s12, 28
	s_add_i32 s13, s12, s13
	s_ashr_i32 s38, s13, 4
	s_and_b32 s13, s13, -16
	s_add_i32 s51, s38, 32
	s_sub_i32 s50, s12, s13
	s_mov_b32 s52, 8
	s_mov_b64 s[12:13], -1
	s_mov_b32 s53, s15

.LBB0_1632:
	s_cmp_lt_i32 s92, 14
	s_cselect_b64 s[0:1], -1, 0
	s_cmp_gt_i32 s93, 13
	s_cselect_b64 s[2:3], -1, 0
	s_and_b64 s[0:1], s[0:1], s[2:3]
	s_andn2_b64 vcc, exec, s[0:1]
	s_cbranch_vccnz .LBB0_1728
	s_cmpk_lg_i32 s33, 0x100
	s_cbranch_scc1 .Lrot13_f
	v_readlane_b32 s2, v254, 15
	s_nop 3
	s_bitcmp1_b32 s2, 5
	s_cbranch_scc0 .Lrot13_f
	s_add_i32 s95, s95, 0x200
.Lrot13_f:
	s_waitcnt vmcnt(31)
	v_mbcnt_lo_u32_b32 v0, -1, 0
	v_mbcnt_hi_u32_b32 v0, -1, v0
	s_movk_i32 s8, 0x1580
	s_cmpk_gt_i32 s95, 0x1ff
	v_mbcnt_lo_u32_b32 v0, -1, 0
	v_mbcnt_hi_u32_b32 v0, -1, v0
	s_cbranch_scc0 .LBB0_1639
	s_add_i32 s0, s95, 0xfffffe00
	s_mov_b64 s[6:7], 0
	s_cmpk_lt_u32 s0, 0x100
	s_mov_b64 s[4:5], 0
	s_cbranch_scc0 .LBB0_1636
	s_and_b32 s1, s95, 7
	s_lshr_b32 s2, s0, 3
	s_cmpk_gt_u32 s0, 0x7f
	s_cselect_b32 s67, 33, 32
	s_add_i32 s3, s2, -16
	s_cmpk_lt_u32 s0, 0x80
	s_cselect_b32 s21, s2, s3
	s_min_u32 s2, s1, 3
	s_cmp_gt_u32 s1, 2
	s_cselect_b32 s10, 10, 12
	s_lshl_b32 s2, s2, 8
	s_mulk_i32 s1, 0x500
	s_add_i32 s1, s2, s1
	s_mov_b64 s[4:5], -1
	s_and_b64 vcc, exec, s[6:7]
	s_cbranch_vccz .LBB0_1640
	s_branch .LBB0_1637

.LBB0_1646:
	s_ashr_i32 s7, s8, 31
	s_lshr_b32 s7, s7, 26
	s_add_i32 s8, s8, s7
	s_ashr_i32 s39, s8, 6
	s_cmp_lt_i32 s10, 0
	s_cselect_b32 s68, s39, s10
	s_add_i32 s40, s2, 0x18000
	s_add_i32 s7, s71, 0x80
	s_mov_b32 s50, s74
	s_mov_b32 s51, s75
	s_mov_b32 m0, s40
	s_add_i32 s41, s2, 0x1a000
	s_waitcnt vmcnt(2)
	s_barrier
	buffer_load_dwordx4 v145, s[48:51], s7 offen lds
	s_mov_b32 m0, s41
	s_add_i32 s42, s2, 0x8000
	buffer_load_dwordx4 v147, s[48:51], s7 offen lds
	s_add_i32 s7, s22, 0x80
	s_mov_b32 m0, s42
	s_add_i32 s43, s2, 0xa000
	buffer_load_dwordx4 v144, s[72:75], s7 offen lds
	s_mov_b32 m0, s43
	s_add_i32 s44, s2, 0x1c000
	buffer_load_dwordx4 v146, s[72:75], s7 offen lds
	s_add_i32 s7, s71, 0x158080
	s_mov_b32 m0, s44
	s_add_i32 s45, s2, 0x1e000
	buffer_load_dwordx4 v145, s[48:51], s7 offen lds
	s_mov_b32 m0, s45
	s_lshl_b32 s46, s6, 6
	buffer_load_dwordx4 v147, s[48:51], s7 offen lds
	v_ashrrev_i32_e32 v1, 6, v0
	s_lshl_b32 s6, s6, 13
	v_and_b32_e32 v2, 48, v0
	v_lshl_add_u32 v3, v1, 10, s6
	v_lshlrev_b32_e32 v4, 6, v0
	s_movk_i32 s6, 0x3c0
	v_and_or_b32 v2, v4, s6, v2
	v_readlane_b32 s6, v254, 16
	s_lshl_b32 s6, s6, 5
	s_and_b32 s47, s6, 0x60
	v_lshlrev_b32_e32 v0, 2, v0
	s_lshr_b32 s6, s47, 3
	v_and_b32_e32 v0, 32, v0
	v_add_lshl_u32 v1, v1, s6, 10
	v_bitop3_b32 v3, v2, v3, v0 bitop3:0xde
	v_bitop3_b32 v0, v2, v1, v0 bitop3:0xde
	s_waitcnt vmcnt(6)
	s_add_i32 s56, s2, 0xc000
	s_cmpk_lt_u32 s89, 0x100
	v_add_u32_e32 v0, 0, v0
	s_mov_b32 s52, 0x8000
	s_mov_b32 s53, 0xc000
	s_cselect_b64 s[6:7], -1, 0
	s_add_i32 s57, s2, 0xe000
	s_ashr_i32 s58, s33, 31
	s_ashr_i32 s59, s95, 31
	v_mov_b64_e32 v[132:133], 0x1ff
	s_cmpk_lg_i32 s33, 0x100
	s_cbranch_scc1 .Lrot13_r
	v_readlane_b32 s8, v254, 15
	s_nop 3
	s_bitcmp1_b32 s8, 5
	s_cbranch_scc0 .Lrot13_r
	s_sub_i32 s95, s95, 0x200
.Lrot13_r:
	v_add_u32_e32 v148, 0x10000, v0
	v_add_u32_e32 v149, 0x14000, v0
	v_add_u32_e32 v150, 0, v3
	v_mov_b32_e32 v151, 0x7f
	v_add_u32_e32 v152, 0x18000, v0
	v_add_u32_e32 v153, 0x1c000, v0
	s_mov_b32 s8, 0x3a800000
	s_mov_b32 s10, 0x3f9837f0
	s_mov_b64 s[12:13], 0x100000
	s_mov_b64 s[14:15], 0x120000
	s_mov_b64 s[16:17], 0x140000
	s_mov_b64 s[18:19], 0x160000
	v_mov_b32_e32 v135, 0
	s_lshl_b32 s20, s47, 2
	s_mov_b32 s60, 0x24000
	s_mov_b32 s61, s1
	s_barrier
	s_branch .LBB0_1649

.LBB0_1649:
	s_add_i32 s61, s61, 1
	s_mul_i32 s23, s61, s58
	s_mul_hi_u32 s24, s61, s33
	s_add_i32 s24, s24, s23
	s_mul_i32 s23, s61, s33
	s_add_u32 s26, s23, s95
	s_addc_u32 s27, s24, s59
	s_cmpk_lg_i32 s33, 0x100
	s_cbranch_scc1 .Lrot13_h
	v_readlane_b32 s23, v254, 15
	s_nop 3
	s_bitcmp1_b32 s23, 5
	s_cbranch_scc0 .Lrot13_h
	s_cmp_lg_u32 s27, 0
	s_cbranch_scc1 .Lrot13_h
	s_cmpk_ge_u32 s26, 0x300
	s_cbranch_scc1 .Lrot13_h
	s_add_u32 s26, s26, 0x200
	s_cmpk_lt_u32 s26, 0x300
	s_cbranch_scc1 .Lrot13_h
	s_sub_u32 s26, s26, 0x300
.Lrot13_h:
	v_cmp_gt_i64_e32 vcc, s[26:27], v[132:133]
	s_mov_b64 s[28:29], -1
	s_cbranch_vccz .LBB0_1652
	s_add_i32 s23, s26, 0xfffffe00
	s_mov_b64 s[28:29], 0
	s_cmpk_gt_i32 s23, 0xff
	s_mov_b64 s[24:25], 0
	s_cbranch_scc1 .LBB0_1652
	s_ashr_i32 s25, s23, 3
	s_lshr_b32 s27, s25, 28
	s_add_i32 s27, s25, s27
	s_and_b32 s24, s26, 7
	s_ashr_i32 s50, s27, 4
	s_and_b32 s27, s27, -16
	s_sub_i32 s63, s25, s27
	s_min_u32 s27, s24, 3
	s_mul_i32 s25, s24, 10
	s_lshl_b32 s27, s27, 1
	s_add_i32 s64, s50, 32
	s_add_i32 s62, s27, s25
	s_cmp_gt_u32 s24, 2
	s_cselect_b32 s65, 10, 12
	s_mov_b64 s[24:25], -1
	s_mov_b32 s66, s23
